# down-GEMM epilogue hand-written (row-group pipelined); SSD pass-3 units dealt XCC-locally and seam 4 L2 write-back skipped under the placement guard
# baseline (speedup 1.0000x reference)
; #define LAS __attribute__((address_space(3)))
; template <bool NEED_C>
; __device__ __forceinline__ void ssd_stage(LAS unsigned char* lds, const bf16_t* XBC, const float* cw, const float* cb, const float* DT, const float* a_log, int c, int g, int tid, int lane, int wave) {
;     ...
;         const int cgi = tid & 63, seg = tid >> 6;
;         int col, tch; LAS unsigned char* tile;
;         if (cgi < 32) { col = g * 256 + cgi * 8; tile = lds + SSD_XT + (cgi >> 4) * 32768; tch = cgi & 15; }
;         else if (cgi < 48) { col = 2048 + g * 128 + (cgi - 32) * 8; tile = lds + SSD_BT; tch = cgi - 32; }
;         else { col = 3072 + g * 128 + (cgi - 48) * 8; tile = lds + SSD_CT; tch = cgi - 48; }
;         if (NEED_C || cgi < 48) {
;             float w[4][8], b[8], xw[3][8];
; #pragma unroll
;             for (int k = 0; k < 4; ++k) { const f32x4 w0 = *(const f32x4*)(cw + k * XBCC + col), w1 = *(const f32x4*)(cw + k * XBCC + col + 4);
; #pragma unroll
;                 for (int e = 0; e < 4; ++e) { w[k][e] = w0[e]; w[k][4 + e] = w1[e]; } }
;             { const f32x4 b0 = *(const f32x4*)(cb + col), b1 = *(const f32x4*)(cb + col + 4);
; #pragma unroll
;               for (int e = 0; e < 4; ++e) { b[e] = b0[e]; b[4 + e] = b1[e]; } }
;             const int t0 = c * 128 + seg * 16;
;             u32x4 raw[19];
; #pragma unroll
;             for (int k = 0; k < 19; ++k) { const int tt = t0 - 3 + k;
;                 if (k >= 3 || tt >= 0) raw[k] = *(const u32x4*)(XBC + (size_t)tt * XBCC + col);
; __global__ void __launch_bounds__(512, 2) k_fwd(Args a_unused) {
;     ...
;         for (int u = c; u < 1024; u += G) { const int ch = u >> 3, g = u & 7;
;             ssd_stage<true>(lds, (const bf16_t*)(ws + WS_XBC), ap->in[6], ap->in[7], (const float*)(ws + WS_DT), ap->in[9], ch, g, tid, lane, wave);
.LBB0_1036:
	s_and_b32 s42, s88, 7
	s_cmpk_lg_i32 s74, 0x100
	s_cbranch_scc1 .Lp4_g_done
	s_bfe_u32 s42, s88, 0x30003
.Lp4_g_done:
	s_and_saveexec_b64 s[4:5], s[38:39]
	s_xor_b64 s[20:21], exec, s[4:5]
	s_cbranch_execz .LBB0_1042
	s_lshl_b32 s1, s42, 7
	s_and_saveexec_b64 s[4:5], s[40:41]
	s_xor_b64 s[58:59], exec, s[4:5]
	v_add_u32_e32 v118, s1, v139
	s_or_saveexec_b64 s[58:59], s[58:59]
	v_mov_b32_e32 v123, s63
	v_mov_b32_e32 v220, v138
	s_xor_b64 exec, exec, s[58:59]
	s_add_i32 s4, 0, 0x10000
	v_add_u32_e32 v118, s1, v140
	v_mov_b32_e32 v123, s4
	v_mov_b32_e32 v220, v1
	s_or_b64 exec, exec, s[58:59]
.LBB0_1042:
	s_andn2_saveexec_b64 s[20:21], s[20:21]
	v_lshl_or_b32 v118, s42, 8, v141
	v_mov_b32_e32 v123, v142
	v_mov_b32_e32 v220, v143
	s_or_b64 exec, exec, s[20:21]
	v_lshlrev_b64 v[10:11], 2, v[118:119]
	s_waitcnt lgkmcnt(0)
	v_lshl_add_u64 v[6:7], s[24:25], 0, v[10:11]
	v_add_co_u32_e32 v4, vcc, 0x4000, v6
	v_lshl_add_u64 v[2:3], v[6:7], 0, s[52:53]
	s_nop 0
	v_addc_co_u32_e32 v5, vcc, 0, v7, vcc
	v_add_co_u32_e32 v12, vcc, s3, v6
	v_lshl_add_u64 v[8:9], v[6:7], 0, s[54:55]
	s_nop 0
	v_addc_co_u32_e32 v13, vcc, 0, v7, vcc
	global_load_dwordx4 v[86:89], v[6:7], off offset:16
	global_load_dwordx4 v[106:109], v[6:7], off
	global_load_dwordx4 v[14:17], v[4:5], off
	s_nop 0
	global_load_dwordx4 v[2:5], v[2:3], off offset:16
	s_nop 0
	global_load_dwordx4 v[110:113], v[12:13], off
	global_load_dwordx4 v[90:93], v[8:9], off offset:16
	v_lshl_add_u64 v[8:9], v[6:7], 0, s[56:57]
	v_add_co_u32_e32 v6, vcc, 0xc000, v6
	v_lshl_add_u64 v[22:23], s[26:27], 0, v[10:11]
	s_nop 0
	v_addc_co_u32_e32 v7, vcc, 0, v7, vcc
	global_load_dwordx4 v[18:21], v[6:7], off
	s_nop 0
	global_load_dwordx4 v[6:9], v[8:9], off offset:16
	s_nop 0
	global_load_dwordx4 v[10:13], v[22:23], off offset:16
	s_nop 0
	global_load_dwordx4 v[22:25], v[22:23], off
	s_ashr_i32 s89, s88, 3
	s_cmpk_lg_i32 s74, 0x100
	s_cbranch_scc1 .Lp4_c_done
	s_and_b32 s89, s88, 7
	s_lshl_b32 s89, s89, 4
	s_bfe_u32 s98, s88, 0x20006
	s_add_i32 s89, s89, s98
	s_lshr_b32 s98, s88, 8
	s_lshl_b32 s98, s98, 2
	s_add_i32 s89, s89, s98
.Lp4_c_done:
	s_lshl_b32 s90, s89, 7
	v_add_u32_e32 v28, s90, v146
	v_lshl_add_u64 v[26:27], v[118:119], 1, s[34:35]
	v_cmp_lt_i32_e32 vcc, -1, v28
	v_mov_b32_e32 v98, 0
	v_mov_b32_e32 v94, 0
	v_mov_b32_e32 v95, 0
	v_mov_b32_e32 v96, 0
	v_mov_b32_e32 v97, 0
	s_and_saveexec_b64 s[20:21], vcc
	s_cbranch_execz .LBB0_1046
	v_mov_b32_e32 v29, v119
	v_lshlrev_b64 v[30:31], 13, v[28:29]
	v_lshl_add_u64 v[30:31], v[26:27], 0, v[30:31]
	global_load_dwordx4 v[94:97], v[30:31], off
